# mixer VALU trimming: 64 dead NaN-canonicalising v_max(x,x) on MFMA outputs and 16 dead K/V phi copies per sweep iteration removed (hazard distances re-checked); on top of stage B
# speedup vs baseline: 1.0042x; 1.0042x over previous
; #define LAS __attribute__((address_space(3)))
; template <bool DIAG> DI void sb_tile(const KFrag& kf, const VFrag& vf, const bf16x8 (&qf)[4], float& F, f32x16& o0, f32x16& o1, int r, int hh) {
;     const f32x16 st = qk_mma(kf, qf);
;     f32x16 w; float M[2];
; #pragma unroll
;     for (int run = 0; run < 2; ++run) {
;         float E = 1.f;
; #pragma unroll
;         for (int e = 7; e >= 0; --e) { const int i = 8 * run + e;
;             const float ex = __builtin_amdgcn_exp2f(__builtin_fminf(st[i], 100.f));
;             float sc = __builtin_amdgcn_rcpf(1.0f + ex), beta = ex * sc;
;             if (DIAG) { if (e + 8 * hh + 16 * run >= r) { sc = 1.f; beta = 0.f; } }
;             w[i] = beta * E; E *= sc; }
; DI void mixer_phase(const Params& p, unsigned char* ldsraw, int vid) {
;     ...
; #pragma unroll 4
;             for (int j = 0; j < 16; ++j) { const int q = wid * 16 + j, tr = q >> 1, half = q & 1;
;                 __builtin_amdgcn_global_load_lds((const unsigned*)(RR + (size_t)(t0 + tr) * 2048 + 1024 + half * 512 + ((ln ^ (tr & 15)) << 3)), (LAS unsigned*)((LAS unsigned char*)ldsraw + 4096 + tr * 2048 + half * 1024), 16, 0, 0); }
;         }
;         const unsigned char* gl = ldsraw + 4096;
;         {
;             f32x16 oA0, oA1, oB0, oB1; ZERO16(oA0); ZERO16(oA1); ZERO16(oB0); ZERO16(oB1);
;             bf16x8 qfA[4], qfB[4];
;             { const bf16_t* qp = QK + ((size_t)(t0 >> 5) * 8 + wid) * 2048 + ln * 8;
; #pragma unroll
;               for (int s = 0; s < 4; ++s) { qfA[s] = *(const bf16x8*)(qp + 512 * s); qfB[s] = *(const bf16x8*)(qp + 8 * 2048 + 512 * s); } }
;             const bf16_t* kb = QK + (size_t)T * 512 + (size_t)wid * 2048 + ln * 8;
;             const bf16_t* vb = VT + (size_t)wid * 2048 + ln * 8;
;             float FA = 1.f, FB = 1.f;
;             KFrag kc, kn; VFrag vc, vn;
;             load_kf(kc, kb + (size_t)((t0 + 32) >> 5) * 16384); load_vf(vc, vb + (size_t)((t0 + 32) >> 5) * 16384); load_kf(kn, kb + (size_t)(t0 >> 5) * 16384); load_vf(vn, vb + (size_t)(t0 >> 5) * 16384);
;             sb_tile<true>(kc, vc, qfB, FB, oB0, oB1, r, hh);
;             kc = kn; vc = vn;
;             int key0 = t0 - 32;
;             if (key0 >= 0) { load_kf(kn, kb + (size_t)(key0 >> 5) * 16384); load_vf(vn, vb + (size_t)(key0 >> 5) * 16384); }
;             sb_tile<true>(kc, vc, qfA, FA, oA0, oA1, r, hh);
.LBB0_397:
	s_ashr_i32 s5, s0, 1
	s_add_i32 s4, s5, s38
	v_bitop3_b32 v0, s5, v205, 14 bitop3:0x6c
	s_ashr_i32 s5, s4, 31
	s_lshl_b64 s[4:5], s[4:5], 12
	v_lshlrev_b32_e32 v0, 3, v0
	s_add_u32 s4, s44, s4
	v_ashrrev_i32_e32 v1, 31, v0
	s_addc_u32 s5, s45, s5
	s_add_i32 s9, s0, 2
	v_lshl_add_u64 v[0:1], v[0:1], 1, s[4:5]
	s_ashr_i32 s5, s9, 1
	s_add_i32 s8, s96, s1
	s_add_i32 s4, s5, s38
	s_add_i32 m0, s8, 0x1000
	v_lshl_add_u64 v[2:3], v[0:1], 0, s[84:85]
	v_bitop3_b32 v4, s5, v205, 15 bitop3:0x6c
	s_ashr_i32 s5, s4, 31
	global_load_lds_dwordx4 v[2:3], off
	s_add_i32 m0, s8, 0x1400
	s_lshl_b64 s[4:5], s[4:5], 12
	v_lshlrev_b32_e32 v2, 3, v4
	s_add_u32 s4, s44, s4
	v_lshl_add_u64 v[0:1], v[0:1], 0, s[86:87]
	v_ashrrev_i32_e32 v3, 31, v2
	s_addc_u32 s5, s45, s5
	global_load_lds_dwordx4 v[0:1], off
	v_lshl_add_u64 v[0:1], v[2:3], 1, s[4:5]
	s_add_i32 m0, s8, 0x1800
	v_lshl_add_u64 v[2:3], v[0:1], 0, s[84:85]
	v_lshl_add_u64 v[0:1], v[0:1], 0, s[86:87]
	global_load_lds_dwordx4 v[2:3], off
	s_add_i32 m0, s8, 0x1c00
	s_addk_i32 s1, 0x1000
	global_load_lds_dwordx4 v[0:1], off
	s_add_i32 s0, s0, 4
	s_cmpk_lg_i32 s1, 0x4000
	s_cbranch_scc1 .LBB0_397
	s_lshl_b32 s4, s72, 1
	s_ashr_i32 s5, s4, 31
	s_lshl_b64 s[0:1], s[4:5], 15
	v_lshlrev_b32_e32 v180, 3, v205
	s_add_u32 s8, s90, s0
	v_ashrrev_i32_e32 v181, 31, v180
	s_addc_u32 s9, s91, s1
	v_lshlrev_b64 v[28:29], 1, v[180:181]
	v_lshl_add_u64 v[44:45], s[8:9], 0, v[28:29]
	s_mov_b32 s5, 0x8000
	s_or_b32 s4, s4, 1
	v_add_co_u32_e32 v4, vcc, s5, v44
	s_ashr_i32 s5, s4, 31
	v_lshl_add_u64 v[184:185], s[54:55], 0, v[28:29]
	s_lshl_b64 s[4:5], s[4:5], 15
	v_lshl_add_u64 v[6:7], v[184:185], 0, s[4:5]
	global_load_dwordx4 v[0:3], v[6:7], off
	v_addc_co_u32_e32 v5, vcc, 0, v45, vcc
	global_load_dwordx4 v[80:83], v[4:5], off
	global_load_dwordx4 v[16:19], v[6:7], off offset:1024
	global_load_dwordx4 v[84:87], v[4:5], off offset:1024
	global_load_dwordx4 v[20:23], v[6:7], off offset:2048
	global_load_dwordx4 v[88:91], v[4:5], off offset:2048
	global_load_dwordx4 v[24:27], v[6:7], off offset:3072
	global_load_dwordx4 v[92:95], v[4:5], off offset:3072
	v_lshl_add_u64 v[186:187], s[62:63], 0, v[28:29]
	v_lshl_add_u64 v[28:29], v[184:185], 0, s[0:1]
	v_lshl_add_u64 v[30:31], v[186:187], 0, s[0:1]
	global_load_dwordx4 v[60:63], v[28:29], off
	global_load_dwordx4 v[56:59], v[28:29], off offset:1024
	global_load_dwordx4 v[52:55], v[28:29], off offset:2048
	global_load_dwordx4 v[48:51], v[28:29], off offset:3072
	global_load_dwordx4 v[76:79], v[30:31], off
	global_load_dwordx4 v[68:71], v[30:31], off offset:1024
	global_load_dwordx4 v[72:75], v[30:31], off offset:2048
	global_load_dwordx4 v[64:67], v[30:31], off offset:3072
	global_load_dwordx4 v[96:99], v[44:45], off
	global_load_dwordx4 v[100:103], v[44:45], off offset:1024
	v_ashrrev_i32_e32 v176, 5, v205
	v_lshlrev_b32_e32 v182, 3, v176
	v_and_b32_e32 v206, 31, v205
	v_or_b32_e32 v46, 7, v182
	v_or_b32_e32 v47, 6, v182
	v_cmp_lt_i32_e64 s[36:37], v46, v206
	v_cmp_lt_i32_e64 s[34:35], v47, v206
	v_add_u32_e32 v104, 23, v182
	v_add_u32_e32 v105, 22, v182
	v_cmp_lt_i32_e64 s[30:31], v104, v206
	v_cmp_lt_i32_e64 s[28:29], v105, v206
	v_add_u32_e32 v47, 21, v182
	v_cmp_lt_i32_e32 vcc, v203, v204
	v_cmp_lt_i32_e64 s[24:25], v47, v206
	v_or_b32_e32 v115, 5, v182
	v_or_b32_e32 v116, 4, v182
	v_add_u32_e32 v112, 16, v182
	v_cmp_lt_i32_e64 s[12:13], v115, v206
	v_or_b32_e32 v117, 3, v182
	v_cmp_lt_i32_e64 s[18:19], v112, v206
	v_cmp_lt_i32_e64 s[14:15], v116, v206
	v_or_b32_e32 v118, 2, v182
	v_add_u32_e32 v110, 18, v182
	v_cmp_lt_i32_e64 s[8:9], v117, v206
	v_or_b32_e32 v119, 1, v182
	v_add_u32_e32 v111, 17, v182
	v_cmp_lt_i32_e64 s[22:23], v110, v206
	v_cmp_lt_i32_e64 s[10:11], v118, v206
	v_cmp_lt_i32_e64 s[16:17], v111, v206
	v_cmp_lt_i32_e64 s[0:1], v182, v206
	s_sub_i32 s39, s38, 32
	s_cmp_lt_i32 s72, 1
	s_waitcnt vmcnt(0)
	v_mfma_f32_32x32x16_bf16 v[0:15], v[0:3], v[80:83], 0
	v_mov_b64_e32 v[126:127], v[78:79]
	v_mov_b64_e32 v[122:123], v[74:75]
	v_mov_b64_e32 v[142:143], v[62:63]
	v_mov_b64_e32 v[138:139], v[58:59]
	v_mov_b64_e32 v[134:135], v[54:55]
	v_mov_b64_e32 v[130:131], v[50:51]
	v_mov_b64_e32 v[120:121], v[72:73]
	v_mfma_f32_32x32x16_bf16 v[0:15], v[16:19], v[84:87], v[0:15]
	v_mov_b64_e32 v[124:125], v[76:77]
	v_mov_b64_e32 v[140:141], v[60:61]
	v_mov_b64_e32 v[136:137], v[56:57]
	v_mov_b64_e32 v[132:133], v[52:53]
	v_mov_b64_e32 v[128:129], v[48:49]
	v_mfma_f32_32x32x16_bf16 v[0:15], v[20:23], v[88:91], v[0:15]
	v_lshl_add_u64 v[20:21], v[186:187], 0, s[4:5]
	global_load_dwordx4 v[16:19], v[20:21], off
	global_load_dwordx4 v[36:39], v[20:21], off offset:1024
	global_load_dwordx4 v[40:43], v[20:21], off offset:2048
	global_load_dwordx4 v[32:35], v[20:21], off offset:3072
	v_cmp_gt_u32_e64 s[4:5], 32, v205
	v_mfma_f32_32x32x16_bf16 v[0:15], v[24:27], v[92:95], v[0:15]
	s_nop 11
	v_min_f32_e32 v7, 0x42c80000, v7
	v_min_f32_e32 v6, 0x42c80000, v6
	v_min_f32_e32 v5, 0x42c80000, v5
	v_min_f32_e32 v4, 0x42c80000, v4
	v_min_f32_e32 v2, 0x42c80000, v2
	v_min_f32_e32 v15, 0x42c80000, v15
	v_exp_f32_e32 v22, v7
	v_exp_f32_e32 v24, v6
	v_exp_f32_e32 v7, v5
	v_exp_f32_e32 v6, v4
	v_exp_f32_e32 v4, v2
	v_exp_f32_e32 v25, v15
	v_min_f32_e32 v1, 0x42c80000, v1
	v_min_f32_e32 v14, 0x42c80000, v14
	v_min_f32_e32 v3, 0x42c80000, v3
	v_exp_f32_e32 v1, v1
	v_exp_f32_e32 v26, v14
	v_min_f32_e32 v0, 0x42c80000, v0
	v_min_f32_e32 v12, 0x42c80000, v12
	v_exp_f32_e32 v5, v3
	v_add_f32_e32 v2, 1.0, v22
	v_add_f32_e32 v3, 1.0, v24
	v_min_f32_e32 v13, 0x42c80000, v13
	v_exp_f32_e32 v0, v0
	v_exp_f32_e32 v20, v12
	v_add_f32_e32 v12, 1.0, v7
	v_add_f32_e32 v27, 1.0, v4
; template <bool DIAG> DI void sb_tile(const KFrag& kf, const VFrag& vf, const bf16x8 (&qf)[4], float& F, f32x16& o0, f32x16& o1, int r, int hh) {
;     const f32x16 st = qk_mma(kf, qf);
;     f32x16 w; float M[2];
; #pragma unroll
;     for (int run = 0; run < 2; ++run) {
;         float E = 1.f;
; #pragma unroll
;         for (int e = 7; e >= 0; --e) { const int i = 8 * run + e;
;             const float ex = __builtin_amdgcn_exp2f(__builtin_fminf(st[i], 100.f));
;             float sc = __builtin_amdgcn_rcpf(1.0f + ex), beta = ex * sc;
;             if (DIAG) { if (e + 8 * hh + 16 * run >= r) { sc = 1.f; beta = 0.f; } }
;             w[i] = beta * E; E *= sc; }
;         M[run] = E;
;     }
;     const float P0 = __shfl_xor(M[0], 32), P1 = __shfl_xor(M[1], 32);
;     const float off1 = F * (hh == 0 ? P1 : 1.f);
;     const float off0 = F * (M[1] * P1) * (hh == 0 ? P0 : 1.f);
;     F = F * (M[0] * P0) * (M[1] * P1);
; #pragma unroll
;     for (int i = 0; i < 16; ++i) w[i] *= (i < 8 ? off0 : off1);
;     pv_mma(vf, w, o0, o1);
; }
; DI void mixer_phase(const Params& p, unsigned char* ldsraw, int vid) {
;     ...
;             if (key0 >= 0) { load_kf(kn, kb + (size_t)(key0 >> 5) * 16384); load_vf(vn, vb + (size_t)(key0 >> 5) * 16384); }
	v_add_f32_e32 v30, 1.0, v25
	v_rcp_f32_e32 v108, v2
	v_rcp_f32_e32 v109, v3
	v_exp_f32_e32 v21, v13
	v_rcp_f32_e32 v15, v12
	v_rcp_f32_e32 v12, v27
	v_rcp_f32_e32 v27, v30
	v_add_f32_e32 v28, 1.0, v1
	v_add_f32_e32 v31, 1.0, v26
	v_min_f32_e32 v9, 0x42c80000, v9
	v_rcp_f32_e32 v3, v28
	v_rcp_f32_e32 v28, v31
	v_exp_f32_e32 v9, v9
	v_min_f32_e32 v8, 0x42c80000, v8
	v_add_f32_e32 v29, 1.0, v0
	v_mul_f32_e32 v22, v22, v108
	v_mul_f32_e32 v24, v24, v109
	v_min_f32_e32 v11, 0x42c80000, v11
	v_exp_f32_e32 v8, v8
	v_add_f32_e32 v13, 1.0, v6
	v_add_f32_e32 v23, 1.0, v5
	v_add_f32_e32 v106, 1.0, v21
	v_add_f32_e32 v107, 1.0, v20
	v_rcp_f32_e32 v2, v29
	v_cndmask_b32_e64 v30, 1.0, v108, s[36:37]
	v_mul_f32_e32 v29, v25, v27
	v_cndmask_b32_e64 v25, 0, v22, s[36:37]
	v_cndmask_b32_e64 v22, 0, v24, s[34:35]
	v_exp_f32_e32 v11, v11
	v_min_f32_e32 v10, 0x42c80000, v10
	v_rcp_f32_e32 v14, v13
	v_rcp_f32_e32 v13, v23
	v_rcp_f32_e32 v23, v106
	v_mul_f32_e32 v24, v30, v22
	v_rcp_f32_e32 v22, v107
	v_exp_f32_e32 v10, v10
	v_mul_f32_e32 v26, v26, v28
	v_cndmask_b32_e64 v105, 0, v29, s[30:31]
	v_add_f32_e32 v29, 1.0, v9
	v_cndmask_b32_e64 v46, 1.0, v27, s[30:31]
	v_cndmask_b32_e64 v26, 0, v26, s[28:29]
	v_rcp_f32_e32 v107, v29
	v_add_f32_e32 v29, 1.0, v8
	v_cndmask_b32_e64 v28, 1.0, v28, s[28:29]
	v_mul_f32_e32 v104, v46, v26
	v_add_u32_e32 v108, 20, v182
	v_add_f32_e32 v26, 1.0, v11
	v_rcp_f32_e32 v106, v29
	v_cndmask_b32_e32 v29, v202, v203, vcc
	v_rcp_f32_e32 v27, v26
	v_add_f32_e32 v26, 1.0, v10
	v_lshlrev_b32_e32 v181, 2, v29
	v_mul_f32_e32 v29, v46, v28
	v_pk_mul_f32 v[20:21], v[20:21], v[22:23]
	v_cndmask_b32_e64 v23, 1.0, v23, s[24:25]
	v_cmp_lt_i32_e64 s[26:27], v108, v206
	v_cndmask_b32_e64 v31, 1.0, v109, s[34:35]
	v_rcp_f32_e32 v26, v26
	v_mul_f32_e32 v28, v23, v29
	v_cndmask_b32_e64 v21, 0, v21, s[24:25]
	v_cndmask_b32_e64 v20, 0, v20, s[26:27]
	v_add_u32_e32 v109, 19, v182
	v_pk_mul_f32 v[112:113], v[20:21], v[28:29]
	v_pk_mul_f32 v[6:7], v[6:7], v[14:15]
	v_mul_f32_e32 v21, v30, v31
	v_cndmask_b32_e64 v15, 1.0, v15, s[12:13]
	v_cndmask_b32_e64 v22, 1.0, v22, s[26:27]
	v_cmp_lt_i32_e64 s[20:21], v109, v206
	v_mul_f32_e32 v20, v15, v21
	v_cndmask_b32_e64 v14, 1.0, v14, s[14:15]
	v_cndmask_b32_e64 v23, 1.0, v27, s[20:21]
	v_mul_f32_e32 v109, v22, v28
	v_cndmask_b32_e64 v7, 0, v7, s[12:13]
	v_cndmask_b32_e64 v6, 0, v6, s[14:15]
	v_pk_mul_f32 v[4:5], v[4:5], v[12:13]
	v_cndmask_b32_e64 v15, 1.0, v13, s[8:9]
	v_mul_f32_e32 v13, v14, v20
	v_cndmask_b32_e64 v46, 1.0, v26, s[22:23]
	v_mul_f32_e32 v108, v23, v109
	v_pk_mul_f32 v[6:7], v[6:7], v[20:21]
	v_cndmask_b32_e64 v21, 1.0, v12, s[10:11]
	v_cndmask_b32_e64 v5, 0, v5, s[8:9]
	v_cndmask_b32_e64 v4, 0, v4, s[10:11]
	v_mul_f32_e32 v12, v15, v13
	v_cmp_lt_i32_e32 vcc, v119, v206
	v_cndmask_b32_e64 v22, 1.0, v107, s[16:17]
	v_mul_f32_e32 v111, v46, v108
	v_pk_mul_f32 v[4:5], v[4:5], v[12:13]
	v_cndmask_b32_e32 v14, 1.0, v3, vcc
	v_mul_f32_e32 v13, v21, v12
	v_cndmask_b32_e64 v23, 1.0, v106, s[18:19]
	v_mul_f32_e32 v110, v22, v111
	v_cndmask_b32_e64 v15, 1.0, v2, s[0:1]
	v_mul_f32_e32 v12, v14, v13
	v_mul_f32_e32 v22, v23, v110
	v_mul_f32_e32 v47, v15, v12
	ds_bpermute_b32 v23, v181, v22
	ds_bpermute_b32 v144, v181, v47
	v_pk_mul_f32 v[0:1], v[0:1], v[2:3]
	v_pk_mul_f32 v[10:11], v[10:11], v[26:27]
	v_cndmask_b32_e32 v1, 0, v1, vcc
	s_waitcnt lgkmcnt(0)
	v_mul_f32_e32 v46, v22, v23
	v_cndmask_b32_e64 v0, 0, v0, s[0:1]
	v_cndmask_b32_e64 v2, 1.0, v144, s[4:5]
	v_pk_mul_f32 v[0:1], v[0:1], v[12:13]
	v_mul_f32_e32 v2, v2, v46
	v_pk_mul_f32 v[0:1], v[0:1], v[2:3] op_sel_hi:[1,0]
	v_pk_mul_f32 v[4:5], v[4:5], v[2:3] op_sel_hi:[1,0]
	v_cvt_pk_bf16_f32 v0, v0, v1
	v_cvt_pk_bf16_f32 v1, v4, v5
	v_pk_mul_f32 v[4:5], v[8:9], v[106:107]
	v_cndmask_b32_e64 v11, 0, v11, s[20:21]
	v_pk_mul_f32 v[6:7], v[6:7], v[2:3] op_sel_hi:[1,0]
	v_pk_mul_f32 v[12:13], v[24:25], v[2:3] op_sel_hi:[1,0]
	v_cndmask_b32_e64 v10, 0, v10, s[22:23]
	v_cndmask_b32_e64 v5, 0, v5, s[16:17]
	v_cndmask_b32_e64 v4, 0, v4, s[18:19]
	v_cndmask_b32_e64 v114, 1.0, v23, s[4:5]
	v_cvt_pk_bf16_f32 v2, v6, v7
	v_cvt_pk_bf16_f32 v3, v12, v13
	v_pk_mul_f32 v[108:109], v[10:11], v[108:109]
	v_pk_mul_f32 v[4:5], v[4:5], v[110:111]
	s_waitcnt vmcnt(3)
	v_mfma_f32_32x32x16_bf16 v[16:31], v[16:19], v[0:3], 0
	v_mul_f32_e64 v106, v114, v4
	v_mul_f32_e64 v107, v114, v5
	v_mul_f32_e64 v104, v114, v104
	v_mul_f32_e64 v105, v114, v105
	v_mov_b64_e32 v[118:119], v[70:71]
	v_mov_b64_e32 v[116:117], v[68:69]
	s_waitcnt vmcnt(1)
	v_mfma_f32_32x32x16_bf16 v[0:15], v[40:43], v[0:3], 0
	v_mul_f32_e64 v42, v114, v108
	v_mul_f32_e64 v43, v114, v109
	v_mul_f32_e64 v108, v114, v112
	v_mul_f32_e64 v109, v114, v113
	v_cvt_pk_bf16_f32 v40, v106, v107
	v_cvt_pk_bf16_f32 v41, v42, v43
	v_cvt_pk_bf16_f32 v42, v108, v109
	v_cvt_pk_bf16_f32 v43, v104, v105
	global_load_dwordx4 v[104:107], v[44:45], off offset:2048
	global_load_dwordx4 v[108:111], v[44:45], off offset:3072
	v_mfma_f32_32x32x16_bf16 v[16:31], v[36:39], v[40:43], v[16:31]
	v_mov_b64_e32 v[114:115], v[66:67]
	v_mov_b64_e32 v[112:113], v[64:65]
	s_waitcnt vmcnt(2)
	v_mfma_f32_32x32x16_bf16 v[0:15], v[32:35], v[40:43], v[0:15]
	s_cbranch_scc1 .LBB0_400
	s_lshr_b32 s72, s39, 5
	s_lshl_b64 s[64:65], s[72:73], 15
	v_lshl_add_u64 v[32:33], v[184:185], 0, s[64:65]
	global_load_dwordx4 v[140:143], v[32:33], off
	global_load_dwordx4 v[136:139], v[32:33], off offset:1024
	global_load_dwordx4 v[132:135], v[32:33], off offset:2048
	global_load_dwordx4 v[128:131], v[32:33], off offset:3072
	v_lshl_add_u64 v[32:33], v[186:187], 0, s[64:65]
	global_load_dwordx4 v[124:127], v[32:33], off
	global_load_dwordx4 v[116:119], v[32:33], off offset:1024
	global_load_dwordx4 v[120:123], v[32:33], off offset:2048
	global_load_dwordx4 v[112:115], v[32:33], off offset:3072
; template <bool DIAG> DI void sb_tile(const KFrag& kf, const VFrag& vf, const bf16x8 (&qf)[4], float& F, f32x16& o0, f32x16& o1, int r, int hh) {
;     const f32x16 st = qk_mma(kf, qf);
;     f32x16 w; float M[2];
; #pragma unroll
;     for (int run = 0; run < 2; ++run) {
;         float E = 1.f;
; #pragma unroll
;         for (int e = 7; e >= 0; --e) { const int i = 8 * run + e;
;             const float ex = __builtin_amdgcn_exp2f(__builtin_fminf(st[i], 100.f));
;             float sc = __builtin_amdgcn_rcpf(1.0f + ex), beta = ex * sc;
;             if (DIAG) { if (e + 8 * hh + 16 * run >= r) { sc = 1.f; beta = 0.f; } }
;             w[i] = beta * E; E *= sc; }
;         M[run] = E;
;     }
; DI void mixer_phase(const Params& p, unsigned char* ldsraw, int vid) {
;     ...
;             sb_tile<true>(kc, vc, qfA, FA, oA0, oA1, r, hh);
;             sb_tile<false>(kc, vc, qfB, FB, oB0, oB1, r, hh);
.LBB0_400:
	v_mul_f32_e32 v32, v47, v144
	v_mul_f32_e32 v151, v32, v46
	v_mfma_f32_32x32x16_bf16 v[32:47], v[60:63], v[96:99], 0
	v_mfma_f32_32x32x16_bf16 v[32:47], v[56:59], v[100:103], v[32:47]
	s_waitcnt vmcnt(1)
	v_mfma_f32_32x32x16_bf16 v[32:47], v[52:55], v[104:107], v[32:47]
	s_waitcnt vmcnt(0)
	v_mfma_f32_32x32x16_bf16 v[32:47], v[48:51], v[108:111], v[32:47]
	s_nop 11
	v_min_f32_e32 v32, 0x42c80000, v32
	v_exp_f32_e32 v162, v32
	v_min_f32_e32 v33, 0x42c80000, v33
	v_exp_f32_e32 v163, v33
	v_add_f32_e32 v32, 1.0, v162
	v_rcp_f32_e32 v164, v32
	v_max_f32_e32 v32, v47, v47
	v_min_f32_e32 v32, 0x42c80000, v32
	v_exp_f32_e32 v32, v32
	v_add_f32_e32 v33, 1.0, v163
	v_rcp_f32_e32 v165, v33
	v_add_f32_e32 v33, 1.0, v32
	v_rcp_f32_e32 v33, v33
	v_min_f32_e32 v39, 0x42c80000, v39
	v_exp_f32_e32 v39, v39
	v_mul_f32_e32 v32, v32, v33
	v_cndmask_b32_e64 v147, 0, v32, s[30:31]
	v_max_f32_e32 v32, v46, v46
	v_min_f32_e32 v32, 0x42c80000, v32
	v_exp_f32_e32 v32, v32
	v_cndmask_b32_e64 v172, 1.0, v33, s[30:31]
	v_add_f32_e32 v144, 1.0, v39
	v_rcp_f32_e32 v144, v144
	v_add_f32_e32 v33, 1.0, v32
	v_rcp_f32_e32 v33, v33
	v_min_f32_e32 v38, 0x42c80000, v38
	v_exp_f32_e32 v38, v38
	v_mul_f32_e32 v39, v39, v144
	v_mul_f32_e32 v32, v32, v33
	v_cndmask_b32_e64 v32, 0, v32, s[28:29]
	v_mul_f32_e32 v146, v172, v32
	v_max_f32_e32 v32, v45, v45
	v_min_f32_e32 v32, 0x42c80000, v32
	v_exp_f32_e32 v191, v32
	v_cndmask_b32_e64 v153, 0, v39, s[36:37]
	v_add_f32_e32 v39, 1.0, v38
	v_add_f32_e32 v32, 1.0, v191
	v_rcp_f32_e32 v193, v32
	v_max_f32_e32 v32, v44, v44
	v_min_f32_e32 v32, 0x42c80000, v32
	v_exp_f32_e32 v190, v32
	s_nop 0
	v_add_f32_e32 v32, 1.0, v190
	v_rcp_f32_e32 v192, v32
	v_max_f32_e32 v32, v43, v43
	v_min_f32_e32 v32, 0x42c80000, v32
	v_exp_f32_e32 v195, v32
	v_rcp_f32_e32 v39, v39
	v_min_f32_e32 v37, 0x42c80000, v37
	v_min_f32_e32 v36, 0x42c80000, v36
	v_add_f32_e32 v32, 1.0, v195
	v_rcp_f32_e32 v197, v32
	v_max_f32_e32 v32, v42, v42
	v_min_f32_e32 v32, 0x42c80000, v32
	v_exp_f32_e32 v194, v32
	v_min_f32_e32 v35, 0x42c80000, v35
	v_min_f32_e32 v34, 0x42c80000, v34
	v_exp_f32_e32 v155, v37
	v_add_f32_e32 v32, 1.0, v194
	v_rcp_f32_e32 v196, v32
	v_max_f32_e32 v32, v41, v41
	v_min_f32_e32 v32, 0x42c80000, v32
	v_exp_f32_e32 v175, v32
	v_exp_f32_e32 v154, v36
	v_exp_f32_e32 v159, v35
	v_exp_f32_e32 v158, v34
	v_add_f32_e32 v32, 1.0, v175
	v_rcp_f32_e32 v189, v32
	v_max_f32_e32 v32, v40, v40
	v_min_f32_e32 v32, 0x42c80000, v32
	v_exp_f32_e32 v174, v32
	v_mul_f32_e32 v38, v38, v39
	v_cndmask_b32_e64 v148, 1.0, v144, s[36:37]
	v_cndmask_b32_e64 v38, 0, v38, s[34:35]
	v_add_f32_e32 v37, 1.0, v155
	v_add_f32_e32 v36, 1.0, v154
	v_add_f32_e32 v35, 1.0, v159
	v_add_f32_e32 v34, 1.0, v158
	v_add_f32_e32 v32, 1.0, v174
	v_cndmask_b32_e64 v144, 1.0, v39, s[34:35]
	v_mul_f32_e32 v152, v148, v38
	v_rcp_f32_e32 v157, v37
	v_rcp_f32_e32 v156, v36
	v_rcp_f32_e32 v161, v35
	v_rcp_f32_e32 v160, v34
	v_cndmask_b32_e64 v198, 1.0, v33, s[28:29]
	v_rcp_f32_e32 v188, v32
	v_mfma_f32_32x32x16_bf16 v[32:47], v[60:63], v[80:83], 0
	v_mfma_f32_32x32x16_bf16 v[32:47], v[56:59], v[84:87], v[32:47]
	v_mfma_f32_32x32x16_bf16 v[32:47], v[52:55], v[88:91], v[32:47]
	v_mfma_f32_32x32x16_bf16 v[32:47], v[48:51], v[92:95], v[32:47]
	s_nop 11
	v_min_f32_e32 v32, 0x42c80000, v32
	v_exp_f32_e32 v58, v32
	v_min_f32_e32 v34, 0x42c80000, v34
	v_exp_f32_e32 v56, v34
	v_add_f32_e32 v32, 1.0, v58
	v_rcp_f32_e32 v48, v32
	v_max_f32_e32 v32, v47, v47
	v_min_f32_e32 v32, 0x42c80000, v32
	v_exp_f32_e32 v171, v32
	v_add_f32_e32 v34, 1.0, v56
	v_min_f32_e32 v39, 0x42c80000, v39
	v_rcp_f32_e32 v52, v34
	v_max_f32_e32 v34, v43, v43
	v_exp_f32_e32 v167, v39
	v_min_f32_e32 v38, 0x42c80000, v38
	v_min_f32_e32 v34, 0x42c80000, v34
	v_exp_f32_e32 v38, v38
	v_add_f32_e32 v32, 1.0, v171
	v_exp_f32_e32 v47, v34
	v_min_f32_e32 v33, 0x42c80000, v33
	v_rcp_f32_e32 v149, v32
	v_max_f32_e32 v32, v46, v46
	v_exp_f32_e32 v59, v33
	v_min_f32_e32 v32, 0x42c80000, v32
	v_add_f32_e32 v39, 1.0, v167
	v_exp_f32_e32 v32, v32
	v_rcp_f32_e32 v169, v39
	v_add_f32_e32 v39, 1.0, v38
	v_min_f32_e32 v37, 0x42c80000, v37
	v_add_f32_e32 v34, 1.0, v47
	v_rcp_f32_e32 v51, v39
	v_exp_f32_e32 v37, v37
	v_rcp_f32_e32 v39, v34
	v_max_f32_e32 v34, v42, v42
	v_add_f32_e32 v33, 1.0, v59
	v_min_f32_e32 v34, 0x42c80000, v34
	v_rcp_f32_e32 v49, v33
	v_add_f32_e32 v33, 1.0, v32
	v_exp_f32_e32 v46, v34
	v_rcp_f32_e32 v145, v33
	v_mul_f32_e32 v166, v38, v51
	v_add_f32_e32 v38, 1.0, v37
	v_rcp_f32_e32 v173, v38
	v_add_f32_e32 v34, 1.0, v46
	v_mul_f32_e32 v170, v32, v145
	v_max_f32_e32 v32, v45, v45
	v_rcp_f32_e32 v38, v34
	v_max_f32_e32 v34, v41, v41
	v_min_f32_e32 v35, 0x42c80000, v35
	v_min_f32_e32 v32, 0x42c80000, v32
	v_min_f32_e32 v34, 0x42c80000, v34
	v_mul_f32_e32 v55, v37, v173
	v_min_f32_e32 v36, 0x42c80000, v36
	v_exp_f32_e32 v57, v35
	v_exp_f32_e32 v37, v32
	v_exp_f32_e32 v61, v34
	v_exp_f32_e32 v50, v36
	v_add_f32_e32 v35, 1.0, v57
	v_add_f32_e32 v32, 1.0, v37
	v_add_f32_e32 v34, 1.0, v61
	v_add_f32_e32 v36, 1.0, v50
	v_rcp_f32_e32 v53, v35
	v_rcp_f32_e32 v33, v32
	v_max_f32_e32 v32, v44, v44
	v_rcp_f32_e32 v35, v34
	v_max_f32_e32 v34, v40, v40
	v_rcp_f32_e32 v168, v36
	v_min_f32_e32 v32, 0x42c80000, v32
	v_min_f32_e32 v34, 0x42c80000, v34
	v_exp_f32_e32 v36, v32
	v_exp_f32_e32 v60, v34
	v_pk_mul_f32 v[40:41], v[46:47], v[38:39]
	v_pk_mul_f32 v[46:47], v[50:51], v[168:169]
	v_add_f32_e32 v32, 1.0, v36
	v_add_f32_e32 v34, 1.0, v60
	v_mov_b32_e32 v199, v47
	v_rcp_f32_e32 v32, v32
	v_rcp_f32_e32 v34, v34
	v_pk_mul_f32 v[50:51], v[172:173], v[198:199]
	v_pk_mul_f32 v[42:43], v[148:149], v[144:145]
	v_mov_b32_e32 v54, v51
; #define MFMA32(a, b, c) __builtin_amdgcn_mfma_f32_32x32x16_bf16((a), (b), (c), 0, 0, 0)
; DI void pv_mma(const VFrag& f, const f32x16& w, f32x16& o0, f32x16& o1) {
; #pragma unroll
;     for (int s = 0; s < 2; ++s) { const bf16x8 pf = pack8(w, s); o0 = MFMA32(f.v[0][s], pf, o0); o1 = MFMA32(f.v[1][s], pf, o1); }
; }
; template <bool DIAG> DI void sb_tile(const KFrag& kf, const VFrag& vf, const bf16x8 (&qf)[4], float& F, f32x16& o0, f32x16& o1, int r, int hh) {
;     ...
;     const float P0 = __shfl_xor(M[0], 32), P1 = __shfl_xor(M[1], 32);
;     const float off1 = F * (hh == 0 ? P1 : 1.f);
;     const float off0 = F * (M[1] * P1) * (hh == 0 ? P0 : 1.f);
;     F = F * (M[0] * P0) * (M[1] * P1);
; #pragma unroll
;     for (int i = 0; i < 16; ++i) w[i] *= (i < 8 ? off0 : off1);
;     pv_mma(vf, w, o0, o1);
	v_pk_mul_f32 v[172:173], v[46:47], v[54:55]
	v_pk_mul_f32 v[46:47], v[56:57], v[52:53]
	v_cndmask_b32_e64 v56, 1.0, v193, s[24:25]
	v_mov_b32_e32 v57, v168
	v_pk_mul_f32 v[54:55], v[58:59], v[48:49]
	v_pk_mul_f32 v[58:59], v[190:191], v[192:193]
	v_pk_mul_f32 v[56:57], v[56:57], v[50:51]
	v_pk_mul_f32 v[44:45], v[36:37], v[32:33]
	v_pk_mul_f32 v[36:37], v[60:61], v[34:35]
	v_cndmask_b32_e64 v60, 1.0, v192, s[26:27]
	v_cndmask_b32_e64 v59, 0, v59, s[24:25]
	v_cndmask_b32_e64 v58, 0, v58, s[26:27]
	v_mov_b32_e32 v62, v56
	v_mov_b32_e32 v63, v50
	v_mov_b32_e32 v61, v53
	v_pk_mul_f32 v[50:51], v[58:59], v[62:63]
	v_pk_mul_f32 v[58:59], v[60:61], v[56:57]
	v_cndmask_b32_e64 v60, 1.0, v196, s[22:23]
	v_mov_b32_e32 v56, v59
	v_pk_mul_f32 v[190:191], v[46:47], v[56:57]
	v_cndmask_b32_e64 v46, 1.0, v197, s[20:21]
	v_mov_b32_e32 v47, v52
	v_pk_mul_f32 v[56:57], v[194:195], v[196:197]
	v_pk_mul_f32 v[46:47], v[46:47], v[58:59]
	v_cndmask_b32_e64 v57, 0, v57, s[20:21]
	v_cndmask_b32_e64 v56, 0, v56, s[22:23]
	v_mov_b32_e32 v61, v49
	v_mov_b32_e32 v52, v46
	v_mov_b32_e32 v53, v58
	v_pk_mul_f32 v[52:53], v[56:57], v[52:53]
	v_pk_mul_f32 v[56:57], v[60:61], v[46:47]
	v_cndmask_b32_e64 v58, 1.0, v189, s[16:17]
	v_mov_b32_e32 v59, v48
	v_pk_mul_f32 v[48:49], v[58:59], v[56:57]
	ds_bpermute_b32 v63, v181, v49
	v_cndmask_b32_e64 v62, 1.0, v188, s[18:19]
	v_mov_b32_e32 v58, v48
	v_pk_mul_f32 v[60:61], v[174:175], v[188:189]
	v_mov_b32_e32 v59, v56
	s_waitcnt lgkmcnt(0)
	v_pk_mul_f32 v[48:49], v[62:63], v[48:49]
	ds_bpermute_b32 v150, v181, v48
	v_cndmask_b32_e64 v61, 0, v61, s[16:17]
	v_cndmask_b32_e64 v60, 0, v60, s[18:19]
	v_pk_mul_f32 v[58:59], v[60:61], v[58:59]
	s_waitcnt lgkmcnt(0)
	v_cndmask_b32_e64 v46, 1.0, v150, s[4:5]
	v_pk_mul_f32 v[174:175], v[48:49], v[150:151]
	v_pk_mul_f32 v[48:49], v[46:47], v[58:59] op_sel_hi:[0,1]
	v_pk_mul_f32 v[52:53], v[46:47], v[52:53] op_sel_hi:[0,1]
	v_pk_mul_f32 v[50:51], v[46:47], v[50:51] op_sel_hi:[0,1]
	v_pk_mul_f32 v[58:59], v[46:47], v[146:147] op_sel_hi:[0,1]
	v_mov_b32_e32 v46, v57
	v_pk_mul_f32 v[192:193], v[54:55], v[46:47]
	v_cndmask_b32_e64 v46, 1.0, v157, s[12:13]
	v_mov_b32_e32 v47, v33
	v_pk_mul_f32 v[46:47], v[46:47], v[42:43]
	v_cvt_pk_bf16_f32 v145, v52, v53
	v_cvt_pk_bf16_f32 v146, v50, v51
	v_cndmask_b32_e64 v50, 1.0, v156, s[14:15]
	v_mov_b32_e32 v53, v42
	v_mov_b32_e32 v51, v32
	v_mov_b32_e32 v42, v47
	v_cvt_pk_bf16_f32 v144, v48, v49
	v_pk_mul_f32 v[48:49], v[154:155], v[156:157]
	v_pk_mul_f32 v[32:33], v[50:51], v[46:47]
	v_pk_mul_f32 v[154:155], v[44:45], v[42:43]
	v_cndmask_b32_e64 v42, 1.0, v161, s[8:9]
	v_mov_b32_e32 v43, v39
	v_pk_mul_f32 v[44:45], v[158:159], v[160:161]
	v_mov_b32_e32 v47, v38
	v_pk_mul_f32 v[38:39], v[42:43], v[32:33]
	v_mov_b32_e32 v52, v46
	v_cndmask_b32_e64 v46, 1.0, v160, s[10:11]
	v_cndmask_b32_e64 v45, 0, v45, s[8:9]
	v_cndmask_b32_e64 v44, 0, v44, s[10:11]
	v_mov_b32_e32 v42, v38
	v_mov_b32_e32 v43, v32
	v_mov_b32_e32 v32, v39
	v_pk_mul_f32 v[42:43], v[44:45], v[42:43]
	v_pk_mul_f32 v[44:45], v[46:47], v[38:39]
	v_pk_mul_f32 v[156:157], v[40:41], v[32:33]
	v_cndmask_b32_e32 v32, 1.0, v165, vcc
	v_mov_b32_e32 v33, v35
	v_pk_mul_f32 v[38:39], v[162:163], v[164:165]
	v_pk_mul_f32 v[32:33], v[32:33], v[44:45]
	v_cndmask_b32_e64 v40, 1.0, v164, s[0:1]
	v_cndmask_b32_e32 v39, 0, v39, vcc
	v_cndmask_b32_e64 v38, 0, v38, s[0:1]
	v_mov_b32_e32 v41, v34
	v_mov_b32_e32 v34, v32
	v_mov_b32_e32 v35, v44
	v_pk_mul_f32 v[34:35], v[38:39], v[34:35]
	v_pk_mul_f32 v[38:39], v[40:41], v[32:33]
	ds_bpermute_b32 v40, v181, v38
	ds_bpermute_b32 v41, v181, v39
	v_cndmask_b32_e64 v49, 0, v49, s[12:13]
	v_cndmask_b32_e64 v48, 0, v48, s[14:15]
	v_pk_mul_f32 v[48:49], v[48:49], v[52:53]
	s_waitcnt lgkmcnt(1)
	v_cndmask_b32_e64 v32, 1.0, v40, s[4:5]
	v_mov_b32_e32 v44, v33
	s_waitcnt lgkmcnt(0)
	v_cndmask_b32_e64 v33, 1.0, v41, s[4:5]
	v_mul_f32_e32 v32, v32, v174
	v_pk_mul_f32 v[158:159], v[38:39], v[40:41]
	v_pk_mul_f32 v[160:161], v[36:37], v[44:45]
	v_pk_mul_f32 v[34:35], v[34:35], v[32:33] op_sel_hi:[1,0]
	v_pk_mul_f32 v[36:37], v[42:43], v[32:33] op_sel_hi:[1,0]
	v_pk_mul_f32 v[38:39], v[48:49], v[32:33] op_sel_hi:[1,0]
	v_pk_mul_f32 v[40:41], v[152:153], v[32:33] op_sel_hi:[1,0]
	v_mul_f32_e32 v148, v151, v33
	v_cvt_pk_bf16_f32 v32, v34, v35
	v_cvt_pk_bf16_f32 v33, v36, v37
	v_cvt_pk_bf16_f32 v34, v38, v39
	v_cvt_pk_bf16_f32 v35, v40, v41
	v_cvt_pk_bf16_f32 v147, v58, v59
	v_cndmask_b32_e64 v150, 1.0, v63, s[4:5]
	v_mfma_f32_32x32x16_bf16 v[48:63], v[76:79], v[32:35], 0
	v_mul_f32_e32 v151, v151, v159
	v_mul_f32_e64 v188, v158, v174
	v_mul_f32_e64 v189, v159, v175
	v_mov_b32_e32 v158, v169
	v_pk_mul_f32 v[158:159], v[158:159], v[166:167] op_sel_hi:[0,1]
	v_pk_mul_f32 v[160:161], v[148:149], v[160:161] op_sel_hi:[0,1]
	v_pk_mul_f32 v[156:157], v[148:149], v[156:157] op_sel_hi:[0,1]
	v_pk_mul_f32 v[154:155], v[148:149], v[154:155] op_sel_hi:[0,1]
	v_mfma_f32_32x32x16_bf16 v[32:47], v[72:75], v[32:35], 0
	v_mfma_f32_32x32x16_bf16 v[48:63], v[68:71], v[144:147], v[48:63]
	v_mfma_f32_32x32x16_bf16 v[32:47], v[64:67], v[144:147], v[32:47]
	v_mul_f32_e32 v144, v150, v151
	v_mul_f32_e64 v146, v192, v144
	v_mul_f32_e64 v147, v193, v144
	v_mul_f32_e64 v150, v190, v144
	v_mul_f32_e64 v151, v191, v144
	v_pk_mul_f32 v[152:153], v[172:173], v[144:145] op_sel_hi:[1,0]
	v_pk_mul_f32 v[158:159], v[158:159], v[144:145] op_sel_hi:[1,0]
	v_mov_b32_e32 v144, v149
	v_pk_mul_f32 v[144:145], v[144:145], v[170:171] op_sel_hi:[0,1]
	v_pk_mul_f32 v[148:149], v[148:149], v[144:145] op_sel_hi:[0,1]
	v_cvt_pk_bf16_f32 v144, v146, v147
	v_cvt_pk_bf16_f32 v145, v150, v151
	v_cvt_pk_bf16_f32 v146, v152, v153
	v_cvt_pk_bf16_f32 v147, v158, v159
	s_nop 1
	v_mfma_f32_32x32x16_bf16 v[16:31], v[76:79], v[144:147], v[16:31]
	v_mfma_f32_32x32x16_bf16 v[0:15], v[72:75], v[144:147], v[0:15]
	v_cvt_pk_bf16_f32 v72, v160, v161
	v_cvt_pk_bf16_f32 v73, v156, v157
	v_cvt_pk_bf16_f32 v74, v154, v155
	v_cvt_pk_bf16_f32 v75, v148, v149
	s_nop 1
	v_mfma_f32_32x32x16_bf16 v[16:31], v[68:71], v[72:75], v[16:31]
	v_mfma_f32_32x32x16_bf16 v[0:15], v[64:67], v[72:75], v[0:15]
	s_branch .LBB0_403

; template <bool DIAG> DI void sb_tile(const KFrag& kf, const VFrag& vf, const bf16x8 (&qf)[4], float& F, f32x16& o0, f32x16& o1, int r, int hh) {
;     const f32x16 st = qk_mma(kf, qf);
;     f32x16 w; float M[2];
; #pragma unroll
;     for (int run = 0; run < 2; ++run) {
;         float E = 1.f;
; #pragma unroll
;         for (int e = 7; e >= 0; --e) { const int i = 8 * run + e;
;             const float ex = __builtin_amdgcn_exp2f(__builtin_fminf(st[i], 100.f));
;             float sc = __builtin_amdgcn_rcpf(1.0f + ex), beta = ex * sc;
;             if (DIAG) { if (e + 8 * hh + 16 * run >= r) { sc = 1.f; beta = 0.f; } }
;             w[i] = beta * E; E *= sc; }
;         M[run] = E;
; DI void mixer_phase(const Params& p, unsigned char* ldsraw, int vid) {
;     ...
;             while (key0 >= 0) {
;                 const bool actA = __builtin_amdgcn_ballot_w64(FA >= SB_STOP_F) != 0ull, actB = __builtin_amdgcn_ballot_w64(FB >= SB_STOP_F) != 0ull;
;                 if (!actA && !actB) break;
;                 kc = kn; vc = vn;
;                 if (key0 >= 32) { load_kf(kn, kb + (size_t)((key0 - 32) >> 5) * 16384); load_vf(vn, vb + (size_t)((key0 - 32) >> 5) * 16384); }
;                 if (actA) sb_tile<false>(kc, vc, qfA, FA, oA0, oA1, r, hh);
.LBB0_403:
	s_cmp_lt_i32 s39, 0
	s_cbranch_scc1 .LBB0_401
	v_cmp_le_f32_e32 vcc, s97, v188
	v_cmp_le_f32_e64 s[0:1], s97, v189
	s_or_b64 s[12:13], vcc, s[0:1]
	s_cmp_lg_u64 vcc, 0
	s_cselect_b64 s[10:11], -1, 0
	s_cmp_lg_u64 s[0:1], 0
	s_cselect_b64 s[8:9], -1, 0
	s_cmp_eq_u64 s[12:13], 0
	s_cselect_b64 s[0:1], -1, 0
	s_and_b64 vcc, exec, s[0:1]
	s_cbranch_vccnz .LBB0_402
	s_cmp_lt_u32 s39, 32
	s_cbranch_scc1 .LBB0_407
	s_sub_i32 s12, s39, 32
	s_lshr_b32 s72, s12, 5
	s_lshl_b64 s[12:13], s[72:73], 15
	v_lshl_add_u64 v[64:65], v[184:185], 0, s[12:13]
	global_load_dwordx4 v[144:147], v[64:65], off
	global_load_dwordx4 v[160:163], v[64:65], off offset:1024
	global_load_dwordx4 v[168:171], v[64:65], off offset:2048
	global_load_dwordx4 v[172:175], v[64:65], off offset:3072
	v_lshl_add_u64 v[64:65], v[186:187], 0, s[12:13]
	global_load_dwordx4 v[164:167], v[64:65], off
	global_load_dwordx4 v[156:159], v[64:65], off offset:1024
	global_load_dwordx4 v[152:155], v[64:65], off offset:2048
	global_load_dwordx4 v[148:151], v[64:65], off offset:3072
.LBB0_407:
	s_andn2_b64 vcc, exec, s[10:11]
	s_cbranch_vccnz .LBB0_409
	v_mfma_f32_32x32x16_bf16 v[64:79], v[140:143], v[96:99], 0
	v_mfma_f32_32x32x16_bf16 v[64:79], v[136:139], v[100:103], v[64:79]
	v_mfma_f32_32x32x16_bf16 v[64:79], v[132:135], v[104:107], v[64:79]
	v_mfma_f32_32x32x16_bf16 v[64:79], v[128:131], v[108:111], v[64:79]
	s_nop 11
	v_min_f32_e32 v71, 0x42c80000, v71
	v_min_f32_e32 v191, 0x42c80000, v65
	v_exp_f32_e32 v65, v71
	v_min_f32_e32 v70, 0x42c80000, v70
	v_min_f32_e32 v64, 0x42c80000, v64
	v_exp_f32_e32 v71, v191
	v_min_f32_e32 v69, 0x42c80000, v69
	v_exp_f32_e32 v207, v70
	v_exp_f32_e32 v70, v64
	v_min_f32_e32 v79, 0x42c80000, v79
	v_min_f32_e32 v68, 0x42c80000, v68
	v_min_f32_e32 v183, 0x42c80000, v67
	v_exp_f32_e32 v67, v69
	v_exp_f32_e32 v79, v79
	v_min_f32_e32 v78, 0x42c80000, v78
	v_min_f32_e32 v190, 0x42c80000, v66
	v_exp_f32_e32 v66, v68
	v_add_f32_e32 v64, 1.0, v65
	v_exp_f32_e32 v78, v78
	v_min_f32_e32 v77, 0x42c80000, v77
	v_exp_f32_e32 v69, v183
	v_rcp_f32_e32 v191, v64
	v_add_f32_e32 v64, 1.0, v71
	v_exp_f32_e32 v77, v77
	v_min_f32_e32 v76, 0x42c80000, v76
	v_exp_f32_e32 v68, v190
	v_rcp_f32_e32 v211, v64
	v_add_f32_e32 v64, 1.0, v70
	v_exp_f32_e32 v76, v76
	v_min_f32_e32 v75, 0x42c80000, v75
	v_add_f32_e32 v190, 1.0, v67
	v_rcp_f32_e32 v213, v64
	v_add_f32_e32 v64, 1.0, v79
	v_exp_f32_e32 v75, v75
	v_min_f32_e32 v74, 0x42c80000, v74
	v_add_f32_e32 v183, 1.0, v207
	v_add_f32_e32 v192, 1.0, v66
	v_rcp_f32_e32 v195, v190
	v_rcp_f32_e32 v190, v64
	v_add_f32_e32 v64, 1.0, v78
	v_exp_f32_e32 v74, v74
	v_min_f32_e32 v73, 0x42c80000, v73
	v_add_f32_e32 v194, 1.0, v69
	v_rcp_f32_e32 v193, v183
	v_rcp_f32_e32 v197, v192
	v_rcp_f32_e32 v192, v64
	v_add_f32_e32 v64, 1.0, v77
	v_exp_f32_e32 v73, v73
	v_min_f32_e32 v72, 0x42c80000, v72
	v_add_f32_e32 v196, 1.0, v68
	v_rcp_f32_e32 v199, v194
	v_rcp_f32_e32 v194, v64
	v_add_f32_e32 v64, 1.0, v76
	v_exp_f32_e32 v72, v72
	v_rcp_f32_e32 v209, v196
	v_rcp_f32_e32 v196, v64
	v_add_f32_e32 v64, 1.0, v75
	v_rcp_f32_e32 v198, v64
	v_add_f32_e32 v64, 1.0, v74
	v_rcp_f32_e32 v208, v64
	v_add_f32_e32 v64, 1.0, v73
	v_pk_mul_f32 v[214:215], v[190:191], v[192:193]
	v_rcp_f32_e32 v210, v64
	v_add_f32_e32 v64, 1.0, v72
	v_pk_mul_f32 v[216:217], v[194:195], v[214:215]
	v_rcp_f32_e32 v212, v64
	v_pk_mul_f32 v[218:219], v[196:197], v[216:217]
	v_mov_b32_e32 v230, v213
	v_pk_mul_f32 v[220:221], v[198:199], v[218:219]
	v_mov_b32_e32 v231, v211
	v_pk_mul_f32 v[222:223], v[208:209], v[220:221]
	v_pk_mul_f32 v[70:71], v[70:71], v[230:231]
	v_pk_mul_f32 v[224:225], v[210:211], v[222:223]
	v_mov_b32_e32 v231, v223
	v_pk_mul_f32 v[226:227], v[212:213], v[224:225]
	ds_bpermute_b32 v228, v181, v226
	ds_bpermute_b32 v229, v181, v227
	v_mov_b32_e32 v230, v225
	v_pk_mul_f32 v[70:71], v[70:71], v[230:231]
	v_mov_b32_e32 v230, v209
	v_mov_b32_e32 v231, v199
	v_pk_mul_f32 v[68:69], v[68:69], v[230:231]
	v_mov_b32_e32 v230, v221
	v_mov_b32_e32 v231, v219
	v_pk_mul_f32 v[68:69], v[68:69], v[230:231]
	v_mov_b32_e32 v230, v197
	v_mov_b32_e32 v231, v195
	s_waitcnt lgkmcnt(1)
	v_cndmask_b32_e64 v183, 1.0, v228, s[4:5]
	s_waitcnt lgkmcnt(0)
	v_pk_mul_f32 v[226:227], v[226:227], v[228:229]
	v_pk_mul_f32 v[66:67], v[66:67], v[230:231]
	v_mov_b32_e32 v230, v217
	v_mov_b32_e32 v231, v215
	v_mul_f32_e32 v64, v207, v193
	v_mul_f32_e32 v78, v78, v192
	v_mul_f32_e32 v192, v188, v183
	v_mul_f32_e32 v183, v188, v226
	v_cndmask_b32_e64 v193, 1.0, v229, s[4:5]
	v_pk_mul_f32 v[66:67], v[66:67], v[230:231]
	v_mov_b32_e32 v230, v191
	v_mul_f32_e32 v228, v193, v183
	v_pk_mul_f32 v[64:65], v[230:231], v[64:65] op_sel_hi:[0,1]
	v_mov_b32_e32 v213, v210
	v_pk_mul_f32 v[70:71], v[70:71], v[228:229] op_sel_hi:[1,0]
	v_pk_mul_f32 v[68:69], v[68:69], v[228:229] op_sel_hi:[1,0]
	v_pk_mul_f32 v[66:67], v[66:67], v[228:229] op_sel_hi:[1,0]
	v_pk_mul_f32 v[228:229], v[64:65], v[228:229] op_sel_hi:[1,0]
	v_pk_mul_f32 v[64:65], v[72:73], v[212:213]
	v_mov_b32_e32 v225, v222
	v_pk_mul_f32 v[64:65], v[64:65], v[224:225]
	v_cvt_pk_bf16_f32 v66, v66, v67
	v_pk_mul_f32 v[72:73], v[192:193], v[64:65] op_sel_hi:[0,1]
	v_cvt_pk_bf16_f32 v64, v70, v71
	v_cvt_pk_bf16_f32 v65, v68, v69
	v_cvt_pk_bf16_f32 v67, v228, v229
	v_mov_b32_e32 v209, v198
	v_mov_b32_e32 v197, v194
	v_mfma_f32_32x32x16_bf16 v[48:63], v[124:127], v[64:67], v[48:63]
	v_mul_f32_e64 v74, v74, v208
	v_mul_f32_e64 v75, v75, v209
	v_mov_b32_e32 v221, v218
	v_mul_f32_e64 v70, v76, v196
	v_mul_f32_e64 v71, v77, v197
	v_mov_b32_e32 v217, v214
	v_pk_mul_f32 v[68:69], v[74:75], v[220:221]
	v_pk_mul_f32 v[70:71], v[70:71], v[216:217]
	v_pk_mul_f32 v[68:69], v[192:193], v[68:69] op_sel_hi:[0,1]
	v_mfma_f32_32x32x16_bf16 v[32:47], v[120:123], v[64:67], v[32:47]
	v_mul_f32_e64 v64, v190, v78
	v_mul_f32_e64 v65, v190, v79
	v_mul_f32_e64 v66, v192, v70
	v_mul_f32_e64 v67, v192, v71
	v_mul_f32_e64 v70, v192, v64
	v_mul_f32_e64 v71, v192, v65
	v_cvt_pk_bf16_f32 v64, v72, v73
	v_cvt_pk_bf16_f32 v65, v68, v69
	v_cvt_pk_bf16_f32 v66, v66, v67
	v_cvt_pk_bf16_f32 v67, v70, v71
	v_mul_f32_e32 v68, v188, v227
	v_mul_f32_e32 v188, v226, v68
	v_mfma_f32_32x32x16_bf16 v[48:63], v[116:119], v[64:67], v[48:63]
	v_mfma_f32_32x32x16_bf16 v[32:47], v[112:115], v[64:67], v[32:47]
; template <bool DIAG> DI void sb_tile(const KFrag& kf, const VFrag& vf, const bf16x8 (&qf)[4], float& F, f32x16& o0, f32x16& o1, int r, int hh) {
;     const f32x16 st = qk_mma(kf, qf);
;     f32x16 w; float M[2];
; #pragma unroll
;     for (int run = 0; run < 2; ++run) {
;         float E = 1.f;
; #pragma unroll
;         for (int e = 7; e >= 0; --e) { const int i = 8 * run + e;
;             const float ex = __builtin_amdgcn_exp2f(__builtin_fminf(st[i], 100.f));
;             float sc = __builtin_amdgcn_rcpf(1.0f + ex), beta = ex * sc;
;             if (DIAG) { if (e + 8 * hh + 16 * run >= r) { sc = 1.f; beta = 0.f; } }
;             w[i] = beta * E; E *= sc; }
;         M[run] = E;
;     }
;     const float P0 = __shfl_xor(M[0], 32), P1 = __shfl_xor(M[1], 32);
;     const float off1 = F * (hh == 0 ? P1 : 1.f);
;     const float off0 = F * (M[1] * P1) * (hh == 0 ? P0 : 1.f);
;     F = F * (M[0] * P0) * (M[1] * P1);
; #pragma unroll
;     for (int i = 0; i < 16; ++i) w[i] *= (i < 8 ? off0 : off1);
;     pv_mma(vf, w, o0, o1);
; }
.LBB0_409:
	s_andn2_b64 vcc, exec, s[8:9]
	s_cbranch_vccnz .LBB0_411
	v_mfma_f32_32x32x16_bf16 v[64:79], v[140:143], v[80:83], 0
	v_mfma_f32_32x32x16_bf16 v[64:79], v[136:139], v[84:87], v[64:79]
	v_mfma_f32_32x32x16_bf16 v[64:79], v[132:135], v[88:91], v[64:79]
	v_mfma_f32_32x32x16_bf16 v[64:79], v[128:131], v[92:95], v[64:79]
	s_nop 11
	v_min_f32_e32 v71, 0x42c80000, v71
	v_min_f32_e32 v130, 0x42c80000, v65
	v_exp_f32_e32 v65, v71
	v_min_f32_e32 v70, 0x42c80000, v70
	v_min_f32_e32 v64, 0x42c80000, v64
	v_exp_f32_e32 v71, v130
	v_exp_f32_e32 v183, v70
	v_exp_f32_e32 v70, v64
	v_min_f32_e32 v79, 0x42c80000, v79
	v_min_f32_e32 v69, 0x42c80000, v69
	v_exp_f32_e32 v79, v79
	v_min_f32_e32 v78, 0x42c80000, v78
	v_min_f32_e32 v68, 0x42c80000, v68
	v_min_f32_e32 v128, 0x42c80000, v67
	v_min_f32_e32 v129, 0x42c80000, v66
	v_exp_f32_e32 v67, v69
	v_add_f32_e32 v64, 1.0, v65
	v_exp_f32_e32 v78, v78
	v_min_f32_e32 v77, 0x42c80000, v77
	v_exp_f32_e32 v66, v68
	v_exp_f32_e32 v68, v129
	v_rcp_f32_e32 v129, v64
	v_add_f32_e32 v64, 1.0, v71
	v_exp_f32_e32 v77, v77
	v_min_f32_e32 v76, 0x42c80000, v76
	v_exp_f32_e32 v69, v128
	v_rcp_f32_e32 v141, v64
	v_add_f32_e32 v64, 1.0, v70
	v_exp_f32_e32 v76, v76
	v_min_f32_e32 v75, 0x42c80000, v75
	v_add_f32_e32 v128, 1.0, v183
	v_rcp_f32_e32 v143, v64
	v_add_f32_e32 v64, 1.0, v79
	v_exp_f32_e32 v75, v75
	v_min_f32_e32 v74, 0x42c80000, v74
	v_add_f32_e32 v130, 1.0, v67
	v_rcp_f32_e32 v131, v128
	v_rcp_f32_e32 v128, v64
	v_add_f32_e32 v64, 1.0, v78
	v_exp_f32_e32 v74, v74
	v_min_f32_e32 v73, 0x42c80000, v73
	v_add_f32_e32 v132, 1.0, v66
	v_rcp_f32_e32 v133, v130
	v_rcp_f32_e32 v130, v64
	v_add_f32_e32 v64, 1.0, v77
	v_exp_f32_e32 v73, v73
	v_min_f32_e32 v72, 0x42c80000, v72
	v_add_f32_e32 v134, 1.0, v69
	v_rcp_f32_e32 v135, v132
	v_rcp_f32_e32 v132, v64
	v_add_f32_e32 v64, 1.0, v76
	v_exp_f32_e32 v72, v72
	v_add_f32_e32 v136, 1.0, v68
	v_rcp_f32_e32 v137, v134
	v_rcp_f32_e32 v134, v64
	v_add_f32_e32 v64, 1.0, v75
	v_rcp_f32_e32 v139, v136
	v_rcp_f32_e32 v136, v64
	v_add_f32_e32 v64, 1.0, v74
	v_rcp_f32_e32 v138, v64
	v_add_f32_e32 v64, 1.0, v73
	v_pk_mul_f32 v[190:191], v[128:129], v[130:131]
	v_rcp_f32_e32 v140, v64
	v_add_f32_e32 v64, 1.0, v72
	v_pk_mul_f32 v[192:193], v[132:133], v[190:191]
	v_rcp_f32_e32 v142, v64
	v_pk_mul_f32 v[194:195], v[134:135], v[192:193]
	v_mov_b32_e32 v214, v143
	v_pk_mul_f32 v[196:197], v[136:137], v[194:195]
	v_mov_b32_e32 v215, v141
	v_pk_mul_f32 v[198:199], v[138:139], v[196:197]
	v_pk_mul_f32 v[70:71], v[70:71], v[214:215]
	v_pk_mul_f32 v[208:209], v[140:141], v[198:199]
	v_mov_b32_e32 v215, v199
	v_pk_mul_f32 v[210:211], v[142:143], v[208:209]
	ds_bpermute_b32 v212, v181, v210
	ds_bpermute_b32 v213, v181, v211
	v_mov_b32_e32 v214, v209
	v_pk_mul_f32 v[70:71], v[70:71], v[214:215]
	v_mov_b32_e32 v214, v139
	v_mov_b32_e32 v215, v137
	v_pk_mul_f32 v[68:69], v[68:69], v[214:215]
	v_mov_b32_e32 v214, v197
	v_mov_b32_e32 v215, v195
	v_pk_mul_f32 v[68:69], v[68:69], v[214:215]
	v_mov_b32_e32 v214, v135
	v_mov_b32_e32 v215, v133
	s_waitcnt lgkmcnt(0)
	v_pk_mul_f32 v[210:211], v[210:211], v[212:213]
	v_pk_mul_f32 v[66:67], v[66:67], v[214:215]
	v_mov_b32_e32 v214, v193
	v_mov_b32_e32 v215, v191
	v_mul_f32_e32 v64, v183, v131
	v_mul_f32_e32 v131, v189, v210
	v_cndmask_b32_e64 v183, 1.0, v213, s[4:5]
	v_pk_mul_f32 v[66:67], v[66:67], v[214:215]
	v_mov_b32_e32 v214, v129
	v_mul_f32_e32 v78, v78, v130
	v_cndmask_b32_e64 v130, 1.0, v212, s[4:5]
	v_mul_f32_e32 v212, v183, v131
	v_pk_mul_f32 v[64:65], v[214:215], v[64:65] op_sel_hi:[0,1]
	v_mov_b32_e32 v143, v140
	v_pk_mul_f32 v[70:71], v[70:71], v[212:213] op_sel_hi:[1,0]
	v_pk_mul_f32 v[68:69], v[68:69], v[212:213] op_sel_hi:[1,0]
	v_pk_mul_f32 v[66:67], v[66:67], v[212:213] op_sel_hi:[1,0]
	v_pk_mul_f32 v[212:213], v[64:65], v[212:213] op_sel_hi:[1,0]
	v_pk_mul_f32 v[64:65], v[72:73], v[142:143]
	v_mov_b32_e32 v209, v198
	v_mul_f32_e32 v130, v189, v130
	v_pk_mul_f32 v[64:65], v[64:65], v[208:209]
	v_cvt_pk_bf16_f32 v66, v66, v67
	v_pk_mul_f32 v[72:73], v[130:131], v[64:65] op_sel_hi:[0,1]
	v_cvt_pk_bf16_f32 v64, v70, v71
	v_cvt_pk_bf16_f32 v65, v68, v69
	v_cvt_pk_bf16_f32 v67, v212, v213
	v_mov_b32_e32 v139, v136
	v_mov_b32_e32 v135, v132
	v_mfma_f32_32x32x16_bf16 v[16:31], v[124:127], v[64:67], v[16:31]
	v_mul_f32_e64 v74, v74, v138
	v_mul_f32_e64 v75, v75, v139
	v_mov_b32_e32 v197, v194
	v_mul_f32_e64 v70, v76, v134
	v_mul_f32_e64 v71, v77, v135
	v_mov_b32_e32 v193, v190
	v_pk_mul_f32 v[68:69], v[74:75], v[196:197]
	v_pk_mul_f32 v[70:71], v[70:71], v[192:193]
	v_pk_mul_f32 v[68:69], v[130:131], v[68:69] op_sel_hi:[0,1]
	v_mfma_f32_32x32x16_bf16 v[0:15], v[120:123], v[64:67], v[0:15]
	v_mul_f32_e64 v64, v128, v78
	v_mul_f32_e64 v65, v128, v79
	v_mul_f32_e64 v66, v130, v70
	v_mul_f32_e64 v67, v130, v71
	v_mul_f32_e64 v70, v130, v64
	v_mul_f32_e64 v71, v130, v65
	v_cvt_pk_bf16_f32 v64, v72, v73
	v_cvt_pk_bf16_f32 v65, v68, v69
	v_cvt_pk_bf16_f32 v66, v66, v67
	v_cvt_pk_bf16_f32 v67, v70, v71
	v_mul_f32_e32 v68, v189, v211
	v_mul_f32_e32 v189, v210, v68
	v_mfma_f32_32x32x16_bf16 v[16:31], v[116:119], v[64:67], v[16:31]
	v_mfma_f32_32x32x16_bf16 v[0:15], v[112:115], v[64:67], v[0:15]
